# speedup vs baseline: 1.0043x; 1.0022x over previous
; __device__ __forceinline__ float siluf_(float x) { return x * sigmoidf_(x); }
; __device__ __forceinline__ u32x2 pack4(float a, float b, float c, float d) { return u32x2{cvtpk(a, b), cvtpk(c, d)}; }
; __device__ __forceinline__ u32x2 pack4(const f32x4& v) { return u32x2{cvtpk(v[0], v[1]), cvtpk(v[2], v[3])}; }
; #define SBAR() __builtin_amdgcn_sched_barrier(0)
; __global__ void __launch_bounds__(512) fwd_megakernel(Params p) {
;     ...
;         #pragma unroll
;         for (int ai = 0; ai < 2; ++ai)
;           #pragma unroll
;           for (int m = 0; m < 4; ++m) { SBAR();
;             int row = brow + ai * 128 + wr * 64 + m * 16 + fr;
;             const float rs = xl[ai * 128 + wr * 64 + m * 16 + fr];
;             bf16* ad = p_act + (long)row * DFF + pn * 128 + wc * 32 + fq * 4;
;             #pragma unroll
;             for (int n = 0; n < 2; ++n) {
;               float a[4];
;               #pragma unroll
;               for (int j = 0; j < 4; ++j) { float g = acc[ai][0][m][n][j] * rs, u = acc[ai][1][m][n][j] * rs; a[j] = siluf_(g) * u; }
;               *reinterpret_cast<u32x2*>(ad + n * 16) = pack4(a[0], a[1], a[2], a[3]);
;             }
.LBB0_664:
	v_mov_b32_e32 v132, v252
	s_waitcnt lgkmcnt(0)
	s_barrier
	s_nop 0
	v_ashrrev_i32_e32 v1, 2, v132
	v_and_b32_e32 v0, 15, v132
	v_and_b32_e32 v1, 0xffffffc0, v1
	v_or_b32_e32 v2, v1, v0
	v_lshlrev_b32_e32 v1, 2, v1
	v_lshlrev_b32_e32 v0, 2, v0
	v_add3_u32 v134, s77, v1, v0
	ds_read_b32 v136, v134
	ds_read_b32 v137, v134 offset:64
	ds_read_b32 v138, v134 offset:128
	ds_read_b32 v139, v134 offset:192
	ds_read_b32 v142, v134 offset:512
	ds_read_b32 v143, v134 offset:576
	ds_read_b32 v145, v134 offset:640
	v_add_u32_e32 v135, s30, v2
	v_mov_b64_e32 v[0:1], s[34:35]
	s_lshl_b32 s4, s63, 7
	s_ashr_i32 s5, s4, 31
	s_lshl_b64 s[4:5], s[4:5], 1
	v_mad_i64_i32 v[2:3], vcc, v135, s61, v[0:1]
	v_lshlrev_b32_e32 v0, 1, v132
	v_lshrrev_b32_e32 v1, 1, v132
	v_and_b32_e32 v0, 32, v0
	v_and_b32_e32 v1, 16, v1
	v_and_b32_e32 v132, 0xc0, v132
	v_or_b32_e32 v0, v0, v1
	v_lshl_add_u64 v[2:3], v[2:3], 0, s[4:5]
	v_or_b32_e32 v132, v132, v0
	s_mov_b32 s30, 0x16000
	s_mov_b32 s31, 0
	s_mov_b64 s[38:39], -1
	v_lshl_add_u64 v[2:3], v[2:3], 0, v[132:133]
	ds_read_b32 v132, v134 offset:704
	s_waitcnt lgkmcnt(0)
	v_mul_f32_e32 v1, v136, v136
	v_mul_f32_e32 v0, 0xbfb8aa3b, v136
	v_rcp_f32_e32 v1, v1
	v_pk_mul_f32 v[128:129], v[124:125], v[128:129]
	v_pk_mul_f32 v[130:131], v[126:127], v[130:131]
	v_pk_mul_f32 v[124:125], v[124:125], v[0:1] op_sel_hi:[1,0]
	v_pk_mul_f32 v[126:127], v[126:127], v[0:1] op_sel_hi:[1,0]
	v_exp_f32_e32 v124, v124
	v_exp_f32_e32 v125, v125
	v_exp_f32_e32 v126, v126
	v_exp_f32_e32 v127, v127
	v_pk_fma_f32 v[124:125], v[124:125], v[0:1], v[0:1] op_sel:[0,1,1] op_sel_hi:[1,1,1]
	v_pk_fma_f32 v[126:127], v[126:127], v[0:1], v[0:1] op_sel:[0,1,1] op_sel_hi:[1,1,1]
	v_rcp_f32_e32 v124, v124
	v_rcp_f32_e32 v125, v125
	v_rcp_f32_e32 v126, v126
	v_rcp_f32_e32 v127, v127
	v_pk_mul_f32 v[128:129], v[128:129], v[124:125]
	v_pk_mul_f32 v[130:131], v[130:131], v[126:127]
	v_pk_mul_f32 v[120:121], v[116:117], v[120:121]
	v_pk_mul_f32 v[122:123], v[118:119], v[122:123]
	v_pk_mul_f32 v[116:117], v[116:117], v[0:1] op_sel_hi:[1,0]
	v_pk_mul_f32 v[118:119], v[118:119], v[0:1] op_sel_hi:[1,0]
	v_exp_f32_e32 v116, v116
	v_exp_f32_e32 v117, v117
	v_exp_f32_e32 v118, v118
	v_exp_f32_e32 v119, v119
	v_pk_fma_f32 v[116:117], v[116:117], v[0:1], v[0:1] op_sel:[0,1,1] op_sel_hi:[1,1,1]
	v_pk_fma_f32 v[118:119], v[118:119], v[0:1], v[0:1] op_sel:[0,1,1] op_sel_hi:[1,1,1]
	v_rcp_f32_e32 v116, v116
	v_rcp_f32_e32 v117, v117
	v_rcp_f32_e32 v118, v118
	v_rcp_f32_e32 v119, v119
	v_pk_mul_f32 v[120:121], v[120:121], v[116:117]
	v_pk_mul_f32 v[122:123], v[122:123], v[118:119]
	v_cvt_pk_bf16_f32 v124, v128, v129
	v_cvt_pk_bf16_f32 v125, v130, v131
	v_cvt_pk_bf16_f32 v126, v120, v121
	v_cvt_pk_bf16_f32 v127, v122, v123
	s_nop 1
	v_permlane16_swap_b32_e32 v124, v126
	v_permlane16_swap_b32_e32 v125, v127
	global_store_dwordx4 v[2:3], v[124:127], off
	v_lshl_add_u64 v[134:135], v[2:3], 0, s[30:31]
	v_mul_f32_e32 v1, v137, v137
	v_mul_f32_e32 v0, 0xbfb8aa3b, v137
	v_rcp_f32_e32 v1, v1
	v_pk_mul_f32 v[112:113], v[108:109], v[112:113]
	v_pk_mul_f32 v[114:115], v[110:111], v[114:115]
	v_pk_mul_f32 v[108:109], v[108:109], v[0:1] op_sel_hi:[1,0]
	v_pk_mul_f32 v[110:111], v[110:111], v[0:1] op_sel_hi:[1,0]
	v_exp_f32_e32 v108, v108
	v_exp_f32_e32 v109, v109
	v_exp_f32_e32 v110, v110
	v_exp_f32_e32 v111, v111
	v_pk_fma_f32 v[108:109], v[108:109], v[0:1], v[0:1] op_sel:[0,1,1] op_sel_hi:[1,1,1]
	v_pk_fma_f32 v[110:111], v[110:111], v[0:1], v[0:1] op_sel:[0,1,1] op_sel_hi:[1,1,1]
	v_rcp_f32_e32 v108, v108
	v_rcp_f32_e32 v109, v109
	v_rcp_f32_e32 v110, v110
	v_rcp_f32_e32 v111, v111
	v_pk_mul_f32 v[112:113], v[112:113], v[108:109]
	v_pk_mul_f32 v[114:115], v[114:115], v[110:111]
	v_pk_mul_f32 v[104:105], v[100:101], v[104:105]
	v_pk_mul_f32 v[106:107], v[102:103], v[106:107]
	v_pk_mul_f32 v[100:101], v[100:101], v[0:1] op_sel_hi:[1,0]
	v_pk_mul_f32 v[102:103], v[102:103], v[0:1] op_sel_hi:[1,0]
	v_exp_f32_e32 v100, v100
	v_exp_f32_e32 v101, v101
	v_exp_f32_e32 v102, v102
	v_exp_f32_e32 v103, v103
	v_pk_fma_f32 v[100:101], v[100:101], v[0:1], v[0:1] op_sel:[0,1,1] op_sel_hi:[1,1,1]
	v_pk_fma_f32 v[102:103], v[102:103], v[0:1], v[0:1] op_sel:[0,1,1] op_sel_hi:[1,1,1]
	v_rcp_f32_e32 v100, v100
	v_rcp_f32_e32 v101, v101
	v_rcp_f32_e32 v102, v102
	v_rcp_f32_e32 v103, v103
	v_pk_mul_f32 v[104:105], v[104:105], v[100:101]
	v_pk_mul_f32 v[106:107], v[106:107], v[102:103]
	v_cvt_pk_bf16_f32 v108, v112, v113
	v_cvt_pk_bf16_f32 v109, v114, v115
	v_cvt_pk_bf16_f32 v110, v104, v105
	v_cvt_pk_bf16_f32 v111, v106, v107
	s_nop 1
	v_permlane16_swap_b32_e32 v108, v110
	v_permlane16_swap_b32_e32 v109, v111
	global_store_dwordx4 v[134:135], v[108:111], off
	v_lshl_add_u64 v[2:3], v[134:135], 0, s[30:31]
	v_mul_f32_e32 v1, v138, v138
	v_mul_f32_e32 v0, 0xbfb8aa3b, v138
	v_rcp_f32_e32 v1, v1
	v_pk_mul_f32 v[96:97], v[92:93], v[96:97]
	v_pk_mul_f32 v[98:99], v[94:95], v[98:99]
	v_pk_mul_f32 v[92:93], v[92:93], v[0:1] op_sel_hi:[1,0]
	v_pk_mul_f32 v[94:95], v[94:95], v[0:1] op_sel_hi:[1,0]
	v_exp_f32_e32 v92, v92
	v_exp_f32_e32 v93, v93
	v_exp_f32_e32 v94, v94
	v_exp_f32_e32 v95, v95
	v_pk_fma_f32 v[92:93], v[92:93], v[0:1], v[0:1] op_sel:[0,1,1] op_sel_hi:[1,1,1]
	v_pk_fma_f32 v[94:95], v[94:95], v[0:1], v[0:1] op_sel:[0,1,1] op_sel_hi:[1,1,1]
	v_rcp_f32_e32 v92, v92
	v_rcp_f32_e32 v93, v93
	v_rcp_f32_e32 v94, v94
	v_rcp_f32_e32 v95, v95
	v_pk_mul_f32 v[96:97], v[96:97], v[92:93]
	v_pk_mul_f32 v[98:99], v[98:99], v[94:95]
	v_pk_mul_f32 v[88:89], v[84:85], v[88:89]
	v_pk_mul_f32 v[90:91], v[86:87], v[90:91]
	v_pk_mul_f32 v[84:85], v[84:85], v[0:1] op_sel_hi:[1,0]
	v_pk_mul_f32 v[86:87], v[86:87], v[0:1] op_sel_hi:[1,0]
; __device__ __forceinline__ float siluf_(float x) { return x * sigmoidf_(x); }
; __device__ __forceinline__ u32x2 pack4(float a, float b, float c, float d) { return u32x2{cvtpk(a, b), cvtpk(c, d)}; }
; __device__ __forceinline__ u32x2 pack4(const f32x4& v) { return u32x2{cvtpk(v[0], v[1]), cvtpk(v[2], v[3])}; }
; #define SBAR() __builtin_amdgcn_sched_barrier(0)
; __global__ void __launch_bounds__(512) fwd_megakernel(Params p) {
;     ...
;         #pragma unroll
;         for (int ai = 0; ai < 2; ++ai)
;           #pragma unroll
;           for (int m = 0; m < 4; ++m) { SBAR();
;             int row = brow + ai * 128 + wr * 64 + m * 16 + fr;
;             const float rs = xl[ai * 128 + wr * 64 + m * 16 + fr];
;             bf16* ad = p_act + (long)row * DFF + pn * 128 + wc * 32 + fq * 4;
;             #pragma unroll
;             for (int n = 0; n < 2; ++n) {
;               float a[4];
;               #pragma unroll
;               for (int j = 0; j < 4; ++j) { float g = acc[ai][0][m][n][j] * rs, u = acc[ai][1][m][n][j] * rs; a[j] = siluf_(g) * u; }
;               *reinterpret_cast<u32x2*>(ad + n * 16) = pack4(a[0], a[1], a[2], a[3]);
;             }
	v_exp_f32_e32 v84, v84
	v_exp_f32_e32 v85, v85
	v_exp_f32_e32 v86, v86
	v_exp_f32_e32 v87, v87
	v_pk_fma_f32 v[84:85], v[84:85], v[0:1], v[0:1] op_sel:[0,1,1] op_sel_hi:[1,1,1]
	v_pk_fma_f32 v[86:87], v[86:87], v[0:1], v[0:1] op_sel:[0,1,1] op_sel_hi:[1,1,1]
	v_rcp_f32_e32 v84, v84
	v_rcp_f32_e32 v85, v85
	v_rcp_f32_e32 v86, v86
	v_rcp_f32_e32 v87, v87
	v_pk_mul_f32 v[88:89], v[88:89], v[84:85]
	v_pk_mul_f32 v[90:91], v[90:91], v[86:87]
	v_cvt_pk_bf16_f32 v92, v96, v97
	v_cvt_pk_bf16_f32 v93, v98, v99
	v_cvt_pk_bf16_f32 v94, v88, v89
	v_cvt_pk_bf16_f32 v95, v90, v91
	s_nop 1
	v_permlane16_swap_b32_e32 v92, v94
	v_permlane16_swap_b32_e32 v93, v95
	global_store_dwordx4 v[2:3], v[92:95], off
	v_lshl_add_u64 v[134:135], v[2:3], 0, s[30:31]
	v_mul_f32_e32 v1, v139, v139
	v_mul_f32_e32 v0, 0xbfb8aa3b, v139
	v_rcp_f32_e32 v1, v1
	v_pk_mul_f32 v[80:81], v[76:77], v[80:81]
	v_pk_mul_f32 v[82:83], v[78:79], v[82:83]
	v_pk_mul_f32 v[76:77], v[76:77], v[0:1] op_sel_hi:[1,0]
	v_pk_mul_f32 v[78:79], v[78:79], v[0:1] op_sel_hi:[1,0]
	v_exp_f32_e32 v76, v76
	v_exp_f32_e32 v77, v77
	v_exp_f32_e32 v78, v78
	v_exp_f32_e32 v79, v79
	v_pk_fma_f32 v[76:77], v[76:77], v[0:1], v[0:1] op_sel:[0,1,1] op_sel_hi:[1,1,1]
	v_pk_fma_f32 v[78:79], v[78:79], v[0:1], v[0:1] op_sel:[0,1,1] op_sel_hi:[1,1,1]
	v_rcp_f32_e32 v76, v76
	v_rcp_f32_e32 v77, v77
	v_rcp_f32_e32 v78, v78
	v_rcp_f32_e32 v79, v79
	v_pk_mul_f32 v[80:81], v[80:81], v[76:77]
	v_pk_mul_f32 v[82:83], v[82:83], v[78:79]
	v_pk_mul_f32 v[72:73], v[64:65], v[72:73]
	v_pk_mul_f32 v[74:75], v[66:67], v[74:75]
	v_pk_mul_f32 v[64:65], v[64:65], v[0:1] op_sel_hi:[1,0]
	v_pk_mul_f32 v[66:67], v[66:67], v[0:1] op_sel_hi:[1,0]
	v_exp_f32_e32 v64, v64
	v_exp_f32_e32 v65, v65
	v_exp_f32_e32 v66, v66
	v_exp_f32_e32 v67, v67
	v_pk_fma_f32 v[64:65], v[64:65], v[0:1], v[0:1] op_sel:[0,1,1] op_sel_hi:[1,1,1]
	v_pk_fma_f32 v[66:67], v[66:67], v[0:1], v[0:1] op_sel:[0,1,1] op_sel_hi:[1,1,1]
	v_rcp_f32_e32 v64, v64
	v_rcp_f32_e32 v65, v65
	v_rcp_f32_e32 v66, v66
	v_rcp_f32_e32 v67, v67
	v_pk_mul_f32 v[72:73], v[72:73], v[64:65]
	v_pk_mul_f32 v[74:75], v[74:75], v[66:67]
	v_cvt_pk_bf16_f32 v76, v80, v81
	v_cvt_pk_bf16_f32 v77, v82, v83
	v_cvt_pk_bf16_f32 v78, v72, v73
	v_cvt_pk_bf16_f32 v79, v74, v75
	s_nop 1
	v_permlane16_swap_b32_e32 v76, v78
	v_permlane16_swap_b32_e32 v77, v79
	global_store_dwordx4 v[134:135], v[76:79], off
	s_mov_b32 s30, 0x6e000
	v_lshl_add_u64 v[2:3], v[134:135], 0, s[30:31]
	v_mul_f32_e32 v1, v142, v142
	v_mul_f32_e32 v0, 0xbfb8aa3b, v142
	v_rcp_f32_e32 v1, v1
	v_pk_mul_f32 v[68:69], v[60:61], v[68:69]
	v_pk_mul_f32 v[70:71], v[62:63], v[70:71]
	v_pk_mul_f32 v[60:61], v[60:61], v[0:1] op_sel_hi:[1,0]
	v_pk_mul_f32 v[62:63], v[62:63], v[0:1] op_sel_hi:[1,0]
	v_exp_f32_e32 v60, v60
	v_exp_f32_e32 v61, v61
	v_exp_f32_e32 v62, v62
	v_exp_f32_e32 v63, v63
	v_pk_fma_f32 v[60:61], v[60:61], v[0:1], v[0:1] op_sel:[0,1,1] op_sel_hi:[1,1,1]
	v_pk_fma_f32 v[62:63], v[62:63], v[0:1], v[0:1] op_sel:[0,1,1] op_sel_hi:[1,1,1]
	v_rcp_f32_e32 v60, v60
	v_rcp_f32_e32 v61, v61
	v_rcp_f32_e32 v62, v62
	v_rcp_f32_e32 v63, v63
	v_pk_mul_f32 v[68:69], v[68:69], v[60:61]
	v_pk_mul_f32 v[70:71], v[70:71], v[62:63]
	v_pk_mul_f32 v[56:57], v[52:53], v[56:57]
	v_pk_mul_f32 v[58:59], v[54:55], v[58:59]
	v_pk_mul_f32 v[52:53], v[52:53], v[0:1] op_sel_hi:[1,0]
	v_pk_mul_f32 v[54:55], v[54:55], v[0:1] op_sel_hi:[1,0]
	v_exp_f32_e32 v52, v52
	v_exp_f32_e32 v53, v53
	v_exp_f32_e32 v54, v54
	v_exp_f32_e32 v55, v55
	v_pk_fma_f32 v[52:53], v[52:53], v[0:1], v[0:1] op_sel:[0,1,1] op_sel_hi:[1,1,1]
	v_pk_fma_f32 v[54:55], v[54:55], v[0:1], v[0:1] op_sel:[0,1,1] op_sel_hi:[1,1,1]
	v_rcp_f32_e32 v52, v52
	v_rcp_f32_e32 v53, v53
	v_rcp_f32_e32 v54, v54
	v_rcp_f32_e32 v55, v55
	v_pk_mul_f32 v[56:57], v[56:57], v[52:53]
	v_pk_mul_f32 v[58:59], v[58:59], v[54:55]
	v_cvt_pk_bf16_f32 v60, v68, v69
	v_cvt_pk_bf16_f32 v61, v70, v71
	v_cvt_pk_bf16_f32 v62, v56, v57
	v_cvt_pk_bf16_f32 v63, v58, v59
	s_nop 1
	v_permlane16_swap_b32_e32 v60, v62
	v_permlane16_swap_b32_e32 v61, v63
	global_store_dwordx4 v[2:3], v[60:63], off
	s_mov_b32 s30, 0x16000
	v_lshl_add_u64 v[134:135], v[2:3], 0, s[30:31]
	v_mul_f32_e32 v1, v143, v143
	v_mul_f32_e32 v0, 0xbfb8aa3b, v143
	v_rcp_f32_e32 v1, v1
	v_pk_mul_f32 v[48:49], v[44:45], v[48:49]
	v_pk_mul_f32 v[50:51], v[46:47], v[50:51]
	v_pk_mul_f32 v[44:45], v[44:45], v[0:1] op_sel_hi:[1,0]
	v_pk_mul_f32 v[46:47], v[46:47], v[0:1] op_sel_hi:[1,0]
	v_exp_f32_e32 v44, v44
	v_exp_f32_e32 v45, v45
	v_exp_f32_e32 v46, v46
	v_exp_f32_e32 v47, v47
	v_pk_fma_f32 v[44:45], v[44:45], v[0:1], v[0:1] op_sel:[0,1,1] op_sel_hi:[1,1,1]
; __device__ __forceinline__ float siluf_(float x) { return x * sigmoidf_(x); }
; __device__ __forceinline__ u32x2 pack4(float a, float b, float c, float d) { return u32x2{cvtpk(a, b), cvtpk(c, d)}; }
; __device__ __forceinline__ u32x2 pack4(const f32x4& v) { return u32x2{cvtpk(v[0], v[1]), cvtpk(v[2], v[3])}; }
; #define SBAR() __builtin_amdgcn_sched_barrier(0)
; __global__ void __launch_bounds__(512) fwd_megakernel(Params p) {
;     ...
;         #pragma unroll
;         for (int ai = 0; ai < 2; ++ai)
;           #pragma unroll
;           for (int m = 0; m < 4; ++m) { SBAR();
;             int row = brow + ai * 128 + wr * 64 + m * 16 + fr;
;             const float rs = xl[ai * 128 + wr * 64 + m * 16 + fr];
;             bf16* ad = p_act + (long)row * DFF + pn * 128 + wc * 32 + fq * 4;
;             #pragma unroll
;             for (int n = 0; n < 2; ++n) {
;               float a[4];
;               #pragma unroll
;               for (int j = 0; j < 4; ++j) { float g = acc[ai][0][m][n][j] * rs, u = acc[ai][1][m][n][j] * rs; a[j] = siluf_(g) * u; }
;               *reinterpret_cast<u32x2*>(ad + n * 16) = pack4(a[0], a[1], a[2], a[3]);
;             }
	v_pk_fma_f32 v[46:47], v[46:47], v[0:1], v[0:1] op_sel:[0,1,1] op_sel_hi:[1,1,1]
	v_rcp_f32_e32 v44, v44
	v_rcp_f32_e32 v45, v45
	v_rcp_f32_e32 v46, v46
	v_rcp_f32_e32 v47, v47
	v_pk_mul_f32 v[48:49], v[48:49], v[44:45]
	v_pk_mul_f32 v[50:51], v[50:51], v[46:47]
	v_pk_mul_f32 v[40:41], v[36:37], v[40:41]
	v_pk_mul_f32 v[42:43], v[38:39], v[42:43]
	v_pk_mul_f32 v[36:37], v[36:37], v[0:1] op_sel_hi:[1,0]
	v_pk_mul_f32 v[38:39], v[38:39], v[0:1] op_sel_hi:[1,0]
	v_exp_f32_e32 v36, v36
	v_exp_f32_e32 v37, v37
	v_exp_f32_e32 v38, v38
	v_exp_f32_e32 v39, v39
	v_pk_fma_f32 v[36:37], v[36:37], v[0:1], v[0:1] op_sel:[0,1,1] op_sel_hi:[1,1,1]
	v_pk_fma_f32 v[38:39], v[38:39], v[0:1], v[0:1] op_sel:[0,1,1] op_sel_hi:[1,1,1]
	v_rcp_f32_e32 v36, v36
	v_rcp_f32_e32 v37, v37
	v_rcp_f32_e32 v38, v38
	v_rcp_f32_e32 v39, v39
	v_pk_mul_f32 v[40:41], v[40:41], v[36:37]
	v_pk_mul_f32 v[42:43], v[42:43], v[38:39]
	v_cvt_pk_bf16_f32 v44, v48, v49
	v_cvt_pk_bf16_f32 v45, v50, v51
	v_cvt_pk_bf16_f32 v46, v40, v41
	v_cvt_pk_bf16_f32 v47, v42, v43
	s_nop 1
	v_permlane16_swap_b32_e32 v44, v46
	v_permlane16_swap_b32_e32 v45, v47
	global_store_dwordx4 v[134:135], v[44:47], off
	v_lshl_add_u64 v[2:3], v[134:135], 0, s[30:31]
	v_mul_f32_e32 v1, v145, v145
	v_mul_f32_e32 v0, 0xbfb8aa3b, v145
	v_rcp_f32_e32 v1, v1
	v_pk_mul_f32 v[32:33], v[28:29], v[32:33]
	v_pk_mul_f32 v[34:35], v[30:31], v[34:35]
	v_pk_mul_f32 v[28:29], v[28:29], v[0:1] op_sel_hi:[1,0]
	v_pk_mul_f32 v[30:31], v[30:31], v[0:1] op_sel_hi:[1,0]
	v_exp_f32_e32 v28, v28
	v_exp_f32_e32 v29, v29
	v_exp_f32_e32 v30, v30
	v_exp_f32_e32 v31, v31
	v_pk_fma_f32 v[28:29], v[28:29], v[0:1], v[0:1] op_sel:[0,1,1] op_sel_hi:[1,1,1]
	v_pk_fma_f32 v[30:31], v[30:31], v[0:1], v[0:1] op_sel:[0,1,1] op_sel_hi:[1,1,1]
	v_rcp_f32_e32 v28, v28
	v_rcp_f32_e32 v29, v29
	v_rcp_f32_e32 v30, v30
	v_rcp_f32_e32 v31, v31
	v_pk_mul_f32 v[32:33], v[32:33], v[28:29]
	v_pk_mul_f32 v[34:35], v[34:35], v[30:31]
	v_pk_mul_f32 v[24:25], v[20:21], v[24:25]
	v_pk_mul_f32 v[26:27], v[22:23], v[26:27]
	v_pk_mul_f32 v[20:21], v[20:21], v[0:1] op_sel_hi:[1,0]
	v_pk_mul_f32 v[22:23], v[22:23], v[0:1] op_sel_hi:[1,0]
	v_exp_f32_e32 v20, v20
	v_exp_f32_e32 v21, v21
	v_exp_f32_e32 v22, v22
	v_exp_f32_e32 v23, v23
	v_pk_fma_f32 v[20:21], v[20:21], v[0:1], v[0:1] op_sel:[0,1,1] op_sel_hi:[1,1,1]
	v_pk_fma_f32 v[22:23], v[22:23], v[0:1], v[0:1] op_sel:[0,1,1] op_sel_hi:[1,1,1]
	v_rcp_f32_e32 v20, v20
	v_rcp_f32_e32 v21, v21
	v_rcp_f32_e32 v22, v22
	v_rcp_f32_e32 v23, v23
	v_pk_mul_f32 v[24:25], v[24:25], v[20:21]
	v_pk_mul_f32 v[26:27], v[26:27], v[22:23]
	v_cvt_pk_bf16_f32 v28, v32, v33
	v_cvt_pk_bf16_f32 v29, v34, v35
	v_cvt_pk_bf16_f32 v30, v24, v25
	v_cvt_pk_bf16_f32 v31, v26, v27
	s_nop 1
	v_permlane16_swap_b32_e32 v28, v30
	v_permlane16_swap_b32_e32 v29, v31
	global_store_dwordx4 v[2:3], v[28:31], off
	v_lshl_add_u64 v[134:135], v[2:3], 0, s[30:31]
	v_mul_f32_e32 v1, v132, v132
	v_mul_f32_e32 v0, 0xbfb8aa3b, v132
	v_rcp_f32_e32 v1, v1
	v_pk_mul_f32 v[16:17], v[12:13], v[16:17]
	v_pk_mul_f32 v[18:19], v[14:15], v[18:19]
	v_pk_mul_f32 v[12:13], v[12:13], v[0:1] op_sel_hi:[1,0]
	v_pk_mul_f32 v[14:15], v[14:15], v[0:1] op_sel_hi:[1,0]
	v_exp_f32_e32 v12, v12
	v_exp_f32_e32 v13, v13
	v_exp_f32_e32 v14, v14
	v_exp_f32_e32 v15, v15
	v_pk_fma_f32 v[12:13], v[12:13], v[0:1], v[0:1] op_sel:[0,1,1] op_sel_hi:[1,1,1]
	v_pk_fma_f32 v[14:15], v[14:15], v[0:1], v[0:1] op_sel:[0,1,1] op_sel_hi:[1,1,1]
	v_rcp_f32_e32 v12, v12
	v_rcp_f32_e32 v13, v13
	v_rcp_f32_e32 v14, v14
	v_rcp_f32_e32 v15, v15
	v_pk_mul_f32 v[16:17], v[16:17], v[12:13]
	v_pk_mul_f32 v[18:19], v[18:19], v[14:15]
	v_pk_mul_f32 v[8:9], v[4:5], v[8:9]
	v_pk_mul_f32 v[10:11], v[6:7], v[10:11]
	v_pk_mul_f32 v[4:5], v[4:5], v[0:1] op_sel_hi:[1,0]
	v_pk_mul_f32 v[6:7], v[6:7], v[0:1] op_sel_hi:[1,0]
	v_exp_f32_e32 v4, v4
	v_exp_f32_e32 v5, v5
	v_exp_f32_e32 v6, v6
	v_exp_f32_e32 v7, v7
	v_pk_fma_f32 v[4:5], v[4:5], v[0:1], v[0:1] op_sel:[0,1,1] op_sel_hi:[1,1,1]
	v_pk_fma_f32 v[6:7], v[6:7], v[0:1], v[0:1] op_sel:[0,1,1] op_sel_hi:[1,1,1]
	v_rcp_f32_e32 v4, v4
	v_rcp_f32_e32 v5, v5
	v_rcp_f32_e32 v6, v6
	v_rcp_f32_e32 v7, v7
	v_pk_mul_f32 v[8:9], v[8:9], v[4:5]
	v_pk_mul_f32 v[10:11], v[10:11], v[6:7]
	v_cvt_pk_bf16_f32 v12, v16, v17
	v_cvt_pk_bf16_f32 v13, v18, v19
	v_cvt_pk_bf16_f32 v14, v8, v9
	v_cvt_pk_bf16_f32 v15, v10, v11
	s_nop 1
	v_permlane16_swap_b32_e32 v12, v14
	v_permlane16_swap_b32_e32 v13, v15
	global_store_dwordx4 v[134:135], v[12:15], off
	s_mov_b32 s4, s62
	s_and_b64 vcc, exec, s[28:29]
	s_cbranch_vccnz .LBB0_689
